# adds one static s_setprio 1 for waves 4-7 at the start of the input-GEMM epilogue (the K-loop's own setprio toggles restore 0)
# speedup vs baseline: 1.0407x; 1.0019x over previous
; #define PG8_BAR __builtin_amdgcn_s_barrier()
; __device__ __forceinline__ void st_bf8(bf16* p, f32x4 a, f32x4 b) { u32x4 w; w.x = pk2(a[0], a[1]); w.y = pk2(a[2], a[3]); w.z = pk2(b[0], b[1]); w.w = pk2(b[2], b[3]); *(u32x4*)p = w; }
; __device__ __forceinline__ f32x4 sigm4(f32x4 v) { return (f32x4){sigm(v[0]), sigm(v[1]), sigm(v[2]), sigm(v[3])}; }
; template <class Epi, class Sched, bool ALIGN_EPI = false, bool SP2 = false>
; __device__ __forceinline__ void gemm_phase(PG8_LAS unsigned char* lds, const Gemm g, const Sched& S, const Epi& E, const int tid_in) {
;     ...
;         if constexpr (ALIGN_EPI) { if (wr == 0) PG8_BAR; }
;         if constexpr (!Epi::AFTER_DRAIN) { E(acc, cur, wr, wc, fr, fq); S.done(cur); }
;     __device__ __forceinline__ void operator()(AccRef acc, const pg8::Unit& u, int wr, int wc, int fr, int fq) const {
;         const int t = u.pn;
;         if (t < 4) { const int c0 = t * 256; EPI_LOOP_P( st_bf8(QD + rw * 1024 + c0 + cl, v0 * qs, v1 * qs); ) }
;         else if (t < 8) { const int c0 = (t - 4) * 256; EPI_LOOP_P( st_bf8(KD + rw * 1024 + c0 + cl, v0, v1); if (row < nvalid) { float* o = okd + rw * 1024 + c0 + cl; *(f32x4*)o = v0; *(f32x4*)(o + 4) = v1; } ) }
;         else if (t < 12) { const int c0 = (t - 8) * 256; EPI_LOOP_P( st_bf8(VD + rw * 1024 + c0 + cl, v0, v1); if (row < nvalid) { float* o = ovd + rw * 1024 + c0 + cl; *(f32x4*)o = v0; *(f32x4*)(o + 4) = v1; } ) }
;         else if (t < 15) { const int c0 = (t - 12) * 256; EPI_LOOP_P( float* o = ZS + rw * 768 + c0 + cl; *(f32x4*)o = v0; *(f32x4*)(o + 4) = v1; ) }
;         else if (t < 19) { const int c0 = (t - 15) * 256; EPI_LOOP_P( st_bf8(GD + rw * 1024 + c0 + cl, sigm4(v0), sigm4(v1)); ) }
;         else { const int c0 = (t - 19) * 256; EPI_LOOP_P( st_bf8(GM + rw * 1024 + c0 + cl, sigm4(v0), sigm4(v1)); ) }
;     }
.LBB0_792:
	v_readlane_b32 s98, v247, 43
	s_cmp_lt_u32 s98, 4
	s_cbranch_scc1 .Lepi_prio_skip
	s_setprio 1
